# v10 plus next sample item's prefetch issued in front of the item's first barrier instead of behind it
# speedup vs baseline: 1.0036x; 1.0030x over previous
.LBB0_311:
	s_mov_b32 s10, s5
	s_add_i32 s5, s5, s20
	s_cmp_ge_i32 s5, s26
	s_cselect_b64 s[2:3], -1, 0
	s_cmp_lt_i32 s5, s26
	s_cselect_b32 s36, s5, 0x1000
	s_ashr_i32 s10, s10, 1
	s_and_b32 s10, s10, -8
	s_ashr_i32 s11, s10, 31
	v_mov_b32_e32 v47, v0
	s_lshl_b64 s[10:11], s[10:11], 11
	s_and_b32 s12, s4, 0x780
	s_or_b32 s10, s10, s12
	v_ashrrev_i32_e32 v134, 6, v47
	s_add_u32 s10, s10, 0x1020000
	v_ashrrev_i32_e32 v135, 31, v134
	s_addc_u32 s11, s11, 0
	v_lshlrev_b64 v[48:49], 11, v[134:135]
	v_lshlrev_b32_e32 v46, 1, v47
	v_lshl_add_u64 v[130:131], s[10:11], 0, v[48:49]
	v_and_b32_e32 v181, 0x7e, v46
	s_lshl_b32 s10, s12, 2
	v_or_b32_e32 v130, v130, v181
	s_add_u32 s10, s72, s10
	v_lshl_add_u64 v[48:49], v[130:131], 1, s[14:15]
	s_addc_u32 s11, s73, 0
	v_lshlrev_b32_e32 v46, 2, v181
	global_load_dword v135, v[48:49], off nt
	global_load_dwordx2 v[132:133], v46, s[10:11]
	v_lshl_add_u32 v46, v47, 2, 0
	v_lshlrev_b32_e32 v48, 16, v177
	v_lshlrev_b32_e32 v50, 16, v178
	v_lshlrev_b32_e32 v49, 16, v137
	ds_write2st64_b32 v46, v48, v50 offset0:67 offset1:75
	v_lshlrev_b32_e32 v48, 16, v176
	s_cmpk_gt_i32 s36, 0x7ff
	ds_write2st64_b32 v46, v179, v180 offset0:51 offset1:59
	ds_write2st64_b32 v46, v49, v48 offset0:32 offset1:40
	s_cbranch_scc1 .Lsamp_nopf
	s_ashr_i32 s10, s36, 1
	s_and_b32 s10, s10, -8
	s_ashr_i32 s11, s10, 31
	s_lshl_b32 s12, s36, 7
	v_mov_b32_e32 v14, v0
	s_lshl_b64 s[10:11], s[10:11], 11
	s_and_b32 s12, s12, 0x780
	s_or_b32 s10, s10, s12
	v_add_u32_e32 v10, 0x200, v14
	s_add_u32 s10, s10, 0x1020000
	v_ashrrev_i32_e32 v4, 7, v14
	v_ashrrev_i32_e32 v10, 7, v10
	s_addc_u32 s11, s11, 0
	v_and_b32_e32 v2, 0x7f, v14
	v_ashrrev_i32_e32 v5, 31, v4
	v_ashrrev_i32_e32 v11, 31, v10
	v_or_b32_e32 v2, s10, v2
	v_mov_b32_e32 v3, s11
	v_lshlrev_b64 v[4:5], 11, v[4:5]
	v_lshlrev_b64 v[10:11], 11, v[10:11]
	v_lshl_add_u64 v[4:5], v[4:5], 0, v[2:3]
	v_lshl_add_u64 v[2:3], v[10:11], 0, v[2:3]
	v_lshl_add_u64 v[6:7], v[4:5], 2, s[28:29]
	v_lshlrev_b64 v[4:5], 1, v[4:5]
	v_lshl_add_u64 v[10:11], v[2:3], 2, s[28:29]
	v_lshlrev_b64 v[2:3], 1, v[2:3]
	s_ashr_i32 s37, s36, 31
	v_lshl_add_u64 v[8:9], s[8:9], 0, v[4:5]
	v_lshl_add_u64 v[4:5], s[6:7], 0, v[4:5]
	v_lshl_add_u64 v[12:13], s[8:9], 0, v[2:3]
	v_lshl_add_u64 v[2:3], s[6:7], 0, v[2:3]
	s_lshl_b64 s[10:11], s[36:37], 16
	global_load_dword v179, v[6:7], off nt
	global_load_ushort v177, v[8:9], off nt
	global_load_ushort v137, v[4:5], off nt
	global_load_dword v180, v[10:11], off nt
	global_load_ushort v178, v[12:13], off nt
	global_load_ushort v176, v[2:3], off nt
	s_add_u32 s10, s60, s10
	v_lshlrev_b32_e32 v2, 4, v14
	v_lshlrev_b32_e32 v4, 5, v14
	s_addc_u32 s11, s61, s11
	v_and_b32_e32 v146, 0x1f0, v2
	v_and_b32_e32 v4, 0xfffffc00, v4
	v_lshl_add_u64 v[2:3], s[10:11], 0, v[146:147]
	v_ashrrev_i32_e32 v5, 31, v4
	v_lshl_add_u64 v[2:3], v[4:5], 2, v[2:3]
	global_load_dwordx4 v[30:33], v[2:3], off nt
	global_load_dwordx4 v[26:29], v[2:3], off offset:512 nt
	global_load_dwordx4 v[22:25], v[2:3], off offset:1024 nt
	global_load_dwordx4 v[18:21], v[2:3], off offset:1536 nt
	global_load_dwordx4 v[14:17], v[2:3], off offset:2048 nt
	global_load_dwordx4 v[10:13], v[2:3], off offset:2560 nt
	global_load_dwordx4 v[6:9], v[2:3], off offset:3072 nt
	s_nop 0
	global_load_dwordx4 v[2:5], v[2:3], off offset:3584 nt
.Lsamp_nopf:
	s_waitcnt lgkmcnt(0)
	s_barrier
.LBB0_313:
	s_movk_i32 s10, 0x80
	v_cmp_gt_i32_e32 vcc, s10, v47
	s_and_saveexec_b64 s[36:37], vcc
	s_cbranch_execz .LBB0_315
	ds_read2st64_b32 v[48:49], v46 offset0:51 offset1:53
	ds_read2st64_b32 v[50:51], v46 offset0:55 offset1:57
	ds_read2st64_b32 v[52:53], v46 offset0:59 offset1:61
	ds_read2st64_b32 v[54:55], v46 offset0:63 offset1:65
	ds_read_b32 v56, v46 offset:17152
	ds_read_b32 v57, v46 offset:17664
	ds_read_b32 v58, v46 offset:18176
	ds_read_b32 v59, v46 offset:18688
	ds_read_b32 v60, v46 offset:19200
	ds_read_b32 v61, v46 offset:19712
	ds_read_b32 v62, v46 offset:20224
	ds_read_b32 v63, v46 offset:20736
	v_mad_u64_u32 v[64:65], s[10:11], v47, 28, v[46:47]
	s_waitcnt lgkmcnt(8)
	v_sub_f32_e32 v98, 1.0, v48
	v_sub_f32_e32 v99, 1.0, v49
	v_sub_f32_e32 v100, 1.0, v50
	v_sub_f32_e32 v101, 1.0, v51
	v_sub_f32_e32 v102, 1.0, v52
	v_sub_f32_e32 v103, 1.0, v53
	v_sub_f32_e32 v104, 1.0, v54
	v_sub_f32_e32 v105, 1.0, v55
	v_mul_f32_e32 v49, v48, v49
	v_mul_f32_e32 v50, v49, v50
	v_mul_f32_e32 v51, v50, v51
	v_mul_f32_e32 v52, v51, v52
	v_mul_f32_e32 v53, v52, v53
	v_mul_f32_e32 v54, v53, v54
	v_mul_f32_e32 v55, v54, v55
	v_rcp_f32_e32 v106, v48
	v_rcp_f32_e32 v107, v49
	v_rcp_f32_e32 v108, v50
	v_rcp_f32_e32 v109, v51
	v_mul_f32_e32 v98, v98, v106
	v_mul_f32_e32 v99, v99, v107
	v_mul_f32_e32 v100, v100, v108
	v_mul_f32_e32 v101, v101, v109
	v_rcp_f32_e32 v106, v52
	v_rcp_f32_e32 v107, v53
	v_rcp_f32_e32 v108, v54
	v_rcp_f32_e32 v109, v55
	v_mul_f32_e32 v102, v102, v106
	v_mul_f32_e32 v103, v103, v107
	v_mul_f32_e32 v104, v104, v108
	v_mul_f32_e32 v105, v105, v109
	s_waitcnt lgkmcnt(0)
	v_mul_f32_e32 v56, v48, v56
	v_mul_f32_e32 v57, v49, v57
	v_mul_f32_e32 v58, v50, v58
	v_mul_f32_e32 v59, v51, v59
	v_mul_f32_e32 v60, v52, v60
	v_mul_f32_e32 v61, v53, v61
	v_mul_f32_e32 v62, v54, v62
	v_mul_f32_e32 v63, v55, v63
	ds_write_b128 v64, v[56:59]
	ds_write_b128 v64, v[60:63] offset:16
	ds_write_b128 v64, v[98:101] offset:4096
	ds_write_b128 v64, v[102:105] offset:4112
	ds_write_b32 v46, v55 offset:12288
